# scan: state decay multiplies split to scalar and interleaved into the MFMA stream of the state update
# speedup vs baseline: 1.0042x; 1.0042x over previous
; DI unsigned cvt_pk_bf16(float lo, float hi) { unsigned r; asm volatile("v_cvt_pk_bf16_f32 %0, %1, %2" : "=v"(r) : "v"(lo), "v"(hi)); return r; }
; #define RT_LGKM(n) do { asm volatile("s_waitcnt lgkmcnt(" #n ")" ::: "memory"); __builtin_amdgcn_sched_barrier(0); } while (0)
; template <int FWD, class BarrierFn>
; DI void scan2_dir(const bf16_t* __restrict__ Qg, const bf16_t* __restrict__ Kg, bf16_t* Vg, bf16_t* Tg, bf16_t* TCB, float* stats, int b, int h, int sl, float lg, char* lds, const BarrierFn& gbar) {
;     ...
;             f32x4 s0 = {0.f, 0.f, 0.f, 0.f}, s1 = {0.f, 0.f, 0.f, 0.f};
;             bf16x8 ak[2], aq0[2], aq1[2], bk[2], bq0[2], bq1[2];
;     ...
;             ST_LOAD(ak, aq0, aq1, 0); ST_LOAD(bk, bq0, bq1, 2);
;             ST_MMA(ak, aq0, aq1); ST_LOAD(ak, aq0, aq1, 4);
;             ST_MMA(bk, bq0, bq1); ST_LOAD(bk, bq0, bq1, 6);
;             ST_MMA(ak, aq0, aq1); ST_MMA(bk, bq0, bq1);
;     ...
;             const int n0 = 16 * qt0 + c, n1 = n0 + 16, mb = 16 * kt + 4 * g;
;             float p0[4], p1[4];
; #pragma unroll
;             for (int jj = 0; jj < 4; ++jj) { const int m = mb + jj; const float wmv = wm[jj];
;                 const bool k0 = FWD ? (m <= n0) : (m > n0), k1 = FWD ? (m <= n1) : (m > n1);
;                 p0[jj] = k0 ? s0[jj] * wmv : 0.f; p1[jj] = k1 ? s1[jj] * wmv : 0.f; }
;             u32x2 w0 = {cvt_pk_bf16(p0[0], p0[1]), cvt_pk_bf16(p0[2], p0[3])}, w1 = {cvt_pk_bf16(p1[0], p1[1]), cvt_pk_bf16(p1[2], p1[3])};
;             *(u32x2*)(lds + P2_OFF + n0 * PRS + mb * 2) = w0; *(u32x2*)(lds + P2_OFF + n1 * PRS + mb * 2) = w1;
;         }
;         f32x4 o[4];
; #pragma unroll
;         for (int nt = 0; nt < 4; ++nt) o[nt] = (f32x4){0.f, 0.f, 0.f, 0.f};
;         {
;             bf16x8 qa[4], qb[4];
;     ...
;             qs_load<0>(qa, qs_b); qs_load<1>(qb, qs_b);
;             RT_LGKM(8); QS_MMA(qa, 0); qs_load<2>(qa, qs_b);
;             RT_LGKM(8); QS_MMA(qb, 1); qs_load<3>(qb, qs_b);
;             RT_LGKM(8); QS_MMA(qa, 2); qs_load<4>(qa, qs_b);
;             RT_LGKM(8); QS_MMA(qb, 3); qs_load<5>(qb, qs_b);
;             RT_LGKM(8); QS_MMA(qa, 4); qs_load<6>(qa, qs_b);
;             RT_LGKM(8); QS_MMA(qb, 5); qs_load<7>(qb, qs_b);
;             RT_LGKM(8); QS_MMA(qa, 6);
;             RT_LGKM(0); QS_MMA(qb, 7);
.LBB0_362:
	ds_read_b128 v[112:115], v214 offset:33792
	ds_read_b128 v[116:119], v214 offset:33856
	ds_read_b128 v[120:123], v215
	ds_read_b128 v[124:127], v215 offset:64
	ds_read_b128 v[128:131], v215 offset:8448
	ds_read_b128 v[132:135], v215 offset:8512
	ds_read_b128 v[136:139], v214 offset:33920
	ds_read_b128 v[140:143], v214 offset:33984
	ds_read_b128 v[218:221], v215 offset:128
	ds_read_b128 v[232:235], v215 offset:192
	ds_read_b128 v[236:239], v215 offset:8576
	ds_read_b128 v[240:243], v215 offset:8640
	s_waitcnt lgkmcnt(9)
	v_mfma_f32_16x16x32_bf16 v[120:123], v[112:115], v[120:123], 0
	s_waitcnt lgkmcnt(7)
	v_mfma_f32_16x16x32_bf16 v[112:115], v[112:115], v[128:131], 0
	ds_read_b128 v[128:131], v214 offset:34048
	ds_read_b128 v[244:247], v214 offset:34112
	ds_read_b128 v[248:251], v215 offset:256
	ds_read_b128 v[222:225], v215 offset:320
	v_mfma_f32_16x16x32_bf16 v[120:123], v[116:119], v[124:127], v[120:123]
	ds_read_b128 v[124:127], v215 offset:8704
	ds_read_b128 v[226:229], v215 offset:8768
	s_waitcnt lgkmcnt(12)
	v_mfma_f32_16x16x32_bf16 v[112:115], v[116:119], v[132:135], v[112:115]
	s_waitcnt lgkmcnt(9)
	v_mfma_f32_16x16x32_bf16 v[116:119], v[136:139], v[218:221], v[120:123]
	s_waitcnt lgkmcnt(7)
	v_mfma_f32_16x16x32_bf16 v[112:115], v[136:139], v[236:239], v[112:115]
	s_nop 0
	ds_read_b128 v[120:123], v214 offset:34176
	ds_read_b128 v[132:135], v214 offset:34240
	ds_read_b128 v[136:139], v215 offset:384
	ds_read_b128 v[218:221], v215 offset:448
	v_mfma_f32_16x16x32_bf16 v[116:119], v[140:143], v[232:235], v[116:119]
	ds_read_b128 v[232:235], v215 offset:8832
	ds_read_b128 v[236:239], v215 offset:8896
	s_waitcnt lgkmcnt(12)
	v_mfma_f32_16x16x32_bf16 v[112:115], v[140:143], v[240:243], v[112:115]
	s_waitcnt lgkmcnt(9)
	v_mfma_f32_16x16x32_bf16 v[116:119], v[128:131], v[248:251], v[116:119]
	s_waitcnt lgkmcnt(7)
	v_mfma_f32_16x16x32_bf16 v[112:115], v[128:131], v[124:127], v[112:115]
	v_mfma_f32_16x16x32_bf16 v[116:119], v[244:247], v[222:225], v[116:119]
	s_waitcnt lgkmcnt(6)
	v_mfma_f32_16x16x32_bf16 v[112:115], v[244:247], v[226:229], v[112:115]
	s_waitcnt lgkmcnt(3)
	v_mfma_f32_16x16x32_bf16 v[116:119], v[120:123], v[136:139], v[116:119]
	s_waitcnt lgkmcnt(1)
	v_mfma_f32_16x16x32_bf16 v[112:115], v[120:123], v[232:235], v[112:115]
	v_mfma_f32_16x16x32_bf16 v[116:119], v[132:135], v[218:221], v[116:119]
	s_waitcnt lgkmcnt(0)
	v_mfma_f32_16x16x32_bf16 v[112:115], v[132:135], v[236:239], v[112:115]
	s_nop 7
	v_mul_f32_e32 v112, v169, v112
	v_mul_f32_e32 v113, v170, v113
	v_mul_f32_e32 v116, v169, v116
	v_cndmask_b32_e64 v120, v112, 0, s[8:9]
	v_mul_f32_e32 v112, v170, v117
	v_cndmask_b32_e64 v117, 0, v113, s[12:13]
	v_mul_f32_e32 v113, v171, v118
	v_mul_f32_e32 v114, v171, v114
	v_cndmask_b32_e64 v116, v116, 0, s[6:7]
	v_cndmask_b32_e64 v112, 0, v112, s[10:11]
	v_cndmask_b32_e64 v113, v113, 0, s[14:15]
	v_cndmask_b32_e64 v118, v114, 0, s[16:17]
	v_mul_f32_e32 v114, v172, v119
	v_mul_f32_e32 v115, v172, v115
	v_cndmask_b32_e64 v114, v114, 0, s[18:19]
	v_cndmask_b32_e64 v115, v115, 0, s[20:21]
	v_cvt_pk_bf16_f32 v112, v116, v112
	v_cvt_pk_bf16_f32 v113, v113, v114
	v_add_u32_e32 v116, v212, v213
	v_cvt_pk_bf16_f32 v114, v120, v117
	v_cvt_pk_bf16_f32 v115, v118, v115
	ds_write_b64 v116, v[112:113]
	ds_write_b64 v216, v[114:115]
	ds_read_b64 v[112:113], v199 offset:0
	ds_read_b64 v[114:115], v199 offset:32
	ds_read_b64 v[116:117], v199 offset:0x2100
	ds_read_b64 v[118:119], v199 offset:0x2120
	ds_read_b64 v[120:121], v199 offset:0x4200
	ds_read_b64 v[122:123], v199 offset:0x4220
	ds_read_b64 v[124:125], v199 offset:0x6300
	ds_read_b64 v[126:127], v199 offset:0x6320
	ds_read_b64 v[128:129], v199 offset:64
	ds_read_b64 v[130:131], v199 offset:0x60
	ds_read_b64 v[132:133], v199 offset:0x2140
	ds_read_b64 v[134:135], v199 offset:0x2160
	ds_read_b64 v[136:137], v199 offset:0x4240
	ds_read_b64 v[138:139], v199 offset:0x4260
	ds_read_b64 v[140:141], v199 offset:0x6340
	ds_read_b64 v[142:143], v199 offset:0x6360
	s_waitcnt lgkmcnt(8)
	v_cvt_pk_bf16_f32 v218, v40, v41
	v_cvt_pk_bf16_f32 v219, v42, v43
	v_cvt_pk_bf16_f32 v220, v44, v45
	v_cvt_pk_bf16_f32 v221, v46, v47
	s_nop 0
	v_mfma_f32_16x16x32_bf16 v[112:115], v[112:115], v[218:221], 0
	v_mfma_f32_16x16x32_bf16 v[116:119], v[116:119], v[218:221], 0
	v_mfma_f32_16x16x32_bf16 v[120:123], v[120:123], v[218:221], 0
	v_mfma_f32_16x16x32_bf16 v[124:127], v[124:127], v[218:221], 0
	ds_read_b64 v[218:219], v199 offset:0x80
	ds_read_b64 v[220:221], v199 offset:0xa0
	ds_read_b64 v[222:223], v199 offset:0x2180
	ds_read_b64 v[224:225], v199 offset:0x21a0
	ds_read_b64 v[226:227], v199 offset:0x4280
	ds_read_b64 v[228:229], v199 offset:0x42a0
	ds_read_b64 v[232:233], v199 offset:0x6380
	ds_read_b64 v[234:235], v199 offset:0x63a0
	s_waitcnt lgkmcnt(8)
	v_cvt_pk_bf16_f32 v236, v52, v53
	v_cvt_pk_bf16_f32 v237, v54, v55
	v_cvt_pk_bf16_f32 v238, v48, v49
	v_cvt_pk_bf16_f32 v239, v50, v51
	s_nop 0
	v_mfma_f32_16x16x32_bf16 v[112:115], v[128:131], v[236:239], v[112:115]
	ds_read_b64 v[128:129], v199 offset:0xc0
	ds_read_b64 v[130:131], v199 offset:0xe0
	v_mfma_f32_16x16x32_bf16 v[116:119], v[132:135], v[236:239], v[116:119]
	ds_read_b64 v[132:133], v199 offset:0x21c0
	ds_read_b64 v[134:135], v199 offset:0x21e0
	v_mfma_f32_16x16x32_bf16 v[120:123], v[136:139], v[236:239], v[120:123]
	ds_read_b64 v[136:137], v199 offset:0x42c0
	ds_read_b64 v[138:139], v199 offset:0x42e0
	v_mfma_f32_16x16x32_bf16 v[124:127], v[140:143], v[236:239], v[124:127]
	ds_read_b64 v[140:141], v199 offset:0x63c0
	ds_read_b64 v[142:143], v199 offset:0x63e0
	s_waitcnt lgkmcnt(8)
; template <int OFF> DI s16x4 tr_rd(unsigned addr) { s16x4 r; asm volatile("ds_read_b64_tr_b16 %0, %1 offset:%2" : "=&v"(r) : "v"(addr), "i"(OFF) : "memory"); return r; }
; #define RT_LGKM(n) do { asm volatile("s_waitcnt lgkmcnt(" #n ")" ::: "memory"); __builtin_amdgcn_sched_barrier(0); } while (0)
; template <int FWD, class BarrierFn>
; DI void scan2_dir(const bf16_t* __restrict__ Qg, const bf16_t* __restrict__ Kg, bf16_t* Vg, bf16_t* Tg, bf16_t* TCB, float* stats, int b, int h, int sl, float lg, char* lds, const BarrierFn& gbar) {
;     ...
;             qs_load<0>(qa, qs_b); qs_load<1>(qb, qs_b);
;             RT_LGKM(8); QS_MMA(qa, 0); qs_load<2>(qa, qs_b);
;             RT_LGKM(8); QS_MMA(qb, 1); qs_load<3>(qb, qs_b);
;             RT_LGKM(8); QS_MMA(qa, 2); qs_load<4>(qa, qs_b);
;             RT_LGKM(8); QS_MMA(qb, 3); qs_load<5>(qb, qs_b);
;             RT_LGKM(8); QS_MMA(qa, 4); qs_load<6>(qa, qs_b);
;             RT_LGKM(8); QS_MMA(qb, 5); qs_load<7>(qb, qs_b);
;             RT_LGKM(8); QS_MMA(qa, 6);
;             RT_LGKM(0); QS_MMA(qb, 7);
;     ...
;         }
;         bf16x8 vf0, vf1;
;         {
;             const s16x4 l0 = tr_rd<0>(vb_tr), h0 = tr_rd<8 * V2RS>(vb_tr), l1 = tr_rd<32 * V2RS>(vb_tr), h1 = tr_rd<40 * V2RS>(vb_tr);
;             KT8 ka, kb2;
;             kt_load<0>(ka, kb_tr);
	v_cvt_pk_bf16_f32 v236, v60, v61
	v_cvt_pk_bf16_f32 v237, v62, v63
	v_cvt_pk_bf16_f32 v238, v56, v57
	v_cvt_pk_bf16_f32 v239, v58, v59
	s_nop 0
	v_mfma_f32_16x16x32_bf16 v[112:115], v[218:221], v[236:239], v[112:115]
	ds_read_b64 v[218:219], v199 offset:0x100
	ds_read_b64 v[220:221], v199 offset:0x120
	v_mfma_f32_16x16x32_bf16 v[116:119], v[222:225], v[236:239], v[116:119]
	ds_read_b64 v[222:223], v199 offset:0x2200
	ds_read_b64 v[224:225], v199 offset:0x2220
	v_mfma_f32_16x16x32_bf16 v[120:123], v[226:229], v[236:239], v[120:123]
	ds_read_b64 v[226:227], v199 offset:0x4300
	ds_read_b64 v[228:229], v199 offset:0x4320
	v_mfma_f32_16x16x32_bf16 v[124:127], v[232:235], v[236:239], v[124:127]
	ds_read_b64 v[232:233], v199 offset:0x6400
	ds_read_b64 v[234:235], v199 offset:0x6420
	s_waitcnt lgkmcnt(8)
	v_cvt_pk_bf16_f32 v236, v68, v69
	v_cvt_pk_bf16_f32 v237, v70, v71
	v_cvt_pk_bf16_f32 v238, v64, v65
	v_cvt_pk_bf16_f32 v239, v66, v67
	s_nop 0
	v_mfma_f32_16x16x32_bf16 v[112:115], v[128:131], v[236:239], v[112:115]
	ds_read_b64 v[128:129], v199 offset:0x140
	ds_read_b64 v[130:131], v199 offset:0x160
	v_mfma_f32_16x16x32_bf16 v[116:119], v[132:135], v[236:239], v[116:119]
	ds_read_b64 v[132:133], v199 offset:0x2240
	ds_read_b64 v[134:135], v199 offset:0x2260
	v_mfma_f32_16x16x32_bf16 v[120:123], v[136:139], v[236:239], v[120:123]
	ds_read_b64 v[136:137], v199 offset:0x4340
	ds_read_b64 v[138:139], v199 offset:0x4360
	v_mfma_f32_16x16x32_bf16 v[124:127], v[140:143], v[236:239], v[124:127]
	ds_read_b64 v[140:141], v199 offset:0x6440
	ds_read_b64 v[142:143], v199 offset:0x6460
	s_waitcnt lgkmcnt(8)
	v_cvt_pk_bf16_f32 v236, v76, v77
	v_cvt_pk_bf16_f32 v237, v78, v79
	v_cvt_pk_bf16_f32 v238, v72, v73
	v_cvt_pk_bf16_f32 v239, v74, v75
	s_nop 0
	v_mfma_f32_16x16x32_bf16 v[112:115], v[218:221], v[236:239], v[112:115]
	ds_read_b64 v[218:219], v199 offset:0x180
	ds_read_b64 v[220:221], v199 offset:0x1a0
	v_mfma_f32_16x16x32_bf16 v[116:119], v[222:225], v[236:239], v[116:119]
	ds_read_b64 v[222:223], v199 offset:0x2280
	ds_read_b64 v[224:225], v199 offset:0x22a0
	v_mfma_f32_16x16x32_bf16 v[120:123], v[226:229], v[236:239], v[120:123]
	ds_read_b64 v[226:227], v199 offset:0x4380
	ds_read_b64 v[228:229], v199 offset:0x43a0
	v_mfma_f32_16x16x32_bf16 v[124:127], v[232:235], v[236:239], v[124:127]
	ds_read_b64 v[232:233], v199 offset:0x6480
	ds_read_b64 v[234:235], v199 offset:0x64a0
	s_waitcnt lgkmcnt(8)
	v_cvt_pk_bf16_f32 v236, v84, v85
	v_cvt_pk_bf16_f32 v237, v86, v87
	v_cvt_pk_bf16_f32 v238, v80, v81
	v_cvt_pk_bf16_f32 v239, v82, v83
	s_nop 0
	v_mfma_f32_16x16x32_bf16 v[112:115], v[128:131], v[236:239], v[112:115]
	ds_read_b64 v[128:129], v199 offset:0x1c0
	ds_read_b64 v[130:131], v199 offset:0x1e0
	v_mfma_f32_16x16x32_bf16 v[120:123], v[136:139], v[236:239], v[120:123]
	ds_read_b64 v[136:137], v199 offset:0x22c0
	ds_read_b64 v[138:139], v199 offset:0x22e0
	v_mfma_f32_16x16x32_bf16 v[124:127], v[140:143], v[236:239], v[124:127]
	ds_read_b64 v[140:141], v199 offset:0x43c0
	ds_read_b64 v[142:143], v199 offset:0x43e0
	v_mfma_f32_16x16x32_bf16 v[116:119], v[132:135], v[236:239], v[116:119]
	ds_read_b64 v[236:237], v199 offset:0x64c0
	ds_read_b64 v[238:239], v199 offset:0x64e0
	s_waitcnt lgkmcnt(8)
	v_cvt_pk_bf16_f32 v132, v92, v93
	v_cvt_pk_bf16_f32 v133, v94, v95
	v_cvt_pk_bf16_f32 v134, v100, v101
	v_cvt_pk_bf16_f32 v135, v102, v103
	s_waitcnt lgkmcnt(0)
	s_nop 0
	v_mfma_f32_16x16x32_bf16 v[112:115], v[218:221], v[132:135], v[112:115]
	v_mfma_f32_16x16x32_bf16 v[116:119], v[222:225], v[132:135], v[116:119]
	v_mfma_f32_16x16x32_bf16 v[120:123], v[226:229], v[132:135], v[120:123]
	v_mfma_f32_16x16x32_bf16 v[124:127], v[232:235], v[132:135], v[124:127]
	v_cvt_pk_bf16_f32 v218, v96, v97
	v_cvt_pk_bf16_f32 v219, v98, v99
	v_cvt_pk_bf16_f32 v220, v88, v89
	v_cvt_pk_bf16_f32 v221, v90, v91
	s_nop 0
	v_mfma_f32_16x16x32_bf16 v[132:135], v[128:131], v[218:221], v[112:115]
	v_mfma_f32_16x16x32_bf16 v[128:131], v[136:139], v[218:221], v[116:119]
	v_mfma_f32_16x16x32_bf16 v[116:119], v[140:143], v[218:221], v[120:123]
	ds_read_b64_tr_b16 v[120:121], v198 offset:0
	ds_read_b64_tr_b16 v[122:123], v198 offset:0x900
	v_mfma_f32_16x16x32_bf16 v[112:115], v[236:239], v[218:221], v[124:127]
	ds_read_b64_tr_b16 v[124:125], v198 offset:0x2400
	ds_read_b64_tr_b16 v[126:127], v198 offset:0x2d00
	ds_read_b64_tr_b16 v[218:219], v168 offset:0
	ds_read_b64_tr_b16 v[220:221], v168 offset:0x1100
	ds_read_b64_tr_b16 v[222:223], v168 offset:0x4400
	ds_read_b64_tr_b16 v[224:225], v168 offset:0x5500
	ds_read_b64_tr_b16 v[226:227], v168 offset:32
	ds_read_b64_tr_b16 v[228:229], v168 offset:0x1120
	ds_read_b64_tr_b16 v[232:233], v168 offset:0x4420
	ds_read_b64_tr_b16 v[234:235], v168 offset:0x5520
	s_waitcnt lgkmcnt(8)
; DI unsigned cvt_pk_bf16(float lo, float hi) { unsigned r; asm volatile("v_cvt_pk_bf16_f32 %0, %1, %2" : "=v"(r) : "v"(lo), "v"(hi)); return r; }
; DI float bf2f(bf16_t b) { return __uint_as_float(((unsigned)b) << 16); }
; template <int OFF> DI s16x4 tr_rd(unsigned addr) { s16x4 r; asm volatile("ds_read_b64_tr_b16 %0, %1 offset:%2" : "=&v"(r) : "v"(addr), "i"(OFF) : "memory"); return r; }
; DI bf16x8 cat(s16x4 l, s16x4 h) { return (bf16x8){l[0], l[1], l[2], l[3], h[0], h[1], h[2], h[3]}; }
; template <int FWD, class BarrierFn>
; DI void scan2_dir(const bf16_t* __restrict__ Qg, const bf16_t* __restrict__ Kg, bf16_t* Vg, bf16_t* Tg, bf16_t* TCB, float* stats, int b, int h, int sl, float lg, char* lds, const BarrierFn& gbar) {
;     ...
;             const s16x4 l0 = tr_rd<0>(vb_tr), h0 = tr_rd<8 * V2RS>(vb_tr), l1 = tr_rd<32 * V2RS>(vb_tr), h1 = tr_rd<40 * V2RS>(vb_tr);
;             KT8 ka, kb2;
;             kt_load<0>(ka, kb_tr);
;             RT_LGKM(8);
;             vf0 = cat(l0, h0); vf1 = cat(l1, h1);
;             bf16x8 vz0, vz1;
;             {
;                 float f[8];
; #pragma unroll
;                 for (int jj = 0; jj < 8; ++jj) f[jj] = bf2f((bf16_t)vf0[jj]) * zt0[jj];
;                 u32x4 w = {cvt_pk_bf16(f[0], f[1]), cvt_pk_bf16(f[2], f[3]), cvt_pk_bf16(f[4], f[5]), cvt_pk_bf16(f[6], f[7])};
;                 vz0 = *reinterpret_cast<bf16x8*>(&w);
; #pragma unroll
;                 for (int jj = 0; jj < 8; ++jj) f[jj] = bf2f((bf16_t)vf1[jj]) * zt1[jj];
;                 u32x4 w2 = {cvt_pk_bf16(f[0], f[1]), cvt_pk_bf16(f[2], f[3]), cvt_pk_bf16(f[4], f[5]), cvt_pk_bf16(f[6], f[7])};
;                 vz1 = *reinterpret_cast<bf16x8*>(&w2);
;             }
; #pragma unroll
;             for (int t = 0; t < 16; ++t) st[t] = st[t] * gC;
;             kt_load<2>(kb2, kb_tr);  RT_LGKM(8); kt_mma(st[0], st[1], ka, vz0, vz1);
;             kt_load<4>(ka, kb_tr);   RT_LGKM(8); kt_mma(st[2], st[3], kb2, vz0, vz1);
;             kt_load<6>(kb2, kb_tr);  RT_LGKM(8); kt_mma(st[4], st[5], ka, vz0, vz1);
;             kt_load<8>(ka, kb_tr);   RT_LGKM(8); kt_mma(st[6], st[7], kb2, vz0, vz1);
;             kt_load<10>(kb2, kb_tr); RT_LGKM(8); kt_mma(st[8], st[9], ka, vz0, vz1);
;             kt_load<12>(ka, kb_tr);  RT_LGKM(8); kt_mma(st[10], st[11], kb2, vz0, vz1);
;             kt_load<14>(kb2, kb_tr); RT_LGKM(8); kt_mma(st[12], st[13], ka, vz0, vz1);
	s_nop 1
	v_lshlrev_b32_e32 v136, 16, v120
	v_and_b32_e32 v137, 0xffff0000, v120
	v_lshlrev_b32_e32 v138, 16, v121
	v_and_b32_e32 v139, 0xffff0000, v121
	v_lshlrev_b32_e32 v140, 16, v122
	v_and_b32_e32 v141, 0xffff0000, v122
	v_lshlrev_b32_e32 v142, 16, v123
	v_and_b32_e32 v143, 0xffff0000, v123
	v_mul_f32_e32 v136, v173, v136
	v_mul_f32_e32 v137, v175, v137
	v_mul_f32_e32 v138, v177, v138
	v_mul_f32_e32 v139, v179, v139
	v_mul_f32_e32 v140, v185, v140
	v_mul_f32_e32 v141, v187, v141
	v_mul_f32_e32 v142, v189, v142
	v_mul_f32_e32 v143, v191, v143
	v_cvt_pk_bf16_f32 v136, v136, v137
	v_cvt_pk_bf16_f32 v137, v138, v139
	v_cvt_pk_bf16_f32 v138, v140, v141
	v_cvt_pk_bf16_f32 v139, v142, v143
	v_lshlrev_b32_e32 v140, 16, v124
	v_and_b32_e32 v141, 0xffff0000, v124
	v_lshlrev_b32_e32 v142, 16, v125
	v_and_b32_e32 v143, 0xffff0000, v125
	v_and_b32_e32 v236, 0xffff0000, v127
	v_mul_f32_e32 v140, v174, v140
	v_mul_f32_e32 v141, v176, v141
	v_mul_f32_e32 v142, v178, v142
	v_mul_f32_e32 v143, v184, v143
	v_lshlrev_b32_e32 v159, 16, v126
	v_and_b32_e32 v180, 0xffff0000, v126
	v_lshlrev_b32_e32 v231, 16, v127
	v_mul_f32_e32 v236, v197, v236
	v_mul_f32_e32 v159, v186, v159
	v_mul_f32_e32 v180, v188, v180
	v_mul_f32_e32 v231, v190, v231
	v_cvt_pk_bf16_f32 v140, v140, v141
	v_cvt_pk_bf16_f32 v141, v142, v143
	v_cvt_pk_bf16_f32 v142, v159, v180
	v_cvt_pk_bf16_f32 v143, v231, v236
	ds_read_b64_tr_b16 v[236:237], v168 offset:64
	ds_read_b64_tr_b16 v[238:239], v168 offset:0x1140
	ds_read_b64_tr_b16 v[240:241], v168 offset:0x4440
	ds_read_b64_tr_b16 v[242:243], v168 offset:0x5540
	ds_read_b64_tr_b16 v[244:245], v168 offset:0x60
	ds_read_b64_tr_b16 v[246:247], v168 offset:0x1160
	ds_read_b64_tr_b16 v[248:249], v168 offset:0x4460
	ds_read_b64_tr_b16 v[250:251], v168 offset:0x5560
	s_waitcnt lgkmcnt(8)
	v_mov_b32_e32 v159, v158
	v_mul_f32_e32 v42, v158, v42
	v_mul_f32_e32 v43, v159, v43
	v_mul_f32_e32 v40, v160, v40
	v_mul_f32_e32 v41, v161, v41
	v_mul_f32_e32 v46, v158, v46
	v_mul_f32_e32 v47, v159, v47
	v_mul_f32_e32 v44, v160, v44
	v_mul_f32_e32 v45, v161, v45
	v_mfma_f32_16x16x32_bf16 v[40:43], v[218:221], v[136:139], v[40:43]
	v_mul_f32_e32 v54, v158, v54
	v_mul_f32_e32 v55, v159, v55
	v_mul_f32_e32 v52, v160, v52
	v_mul_f32_e32 v53, v161, v53
	v_mul_f32_e32 v50, v158, v50
	v_mul_f32_e32 v51, v159, v51
	v_mul_f32_e32 v48, v160, v48
	v_mul_f32_e32 v49, v161, v49
	ds_read_b64_tr_b16 v[218:219], v168 offset:0x80
	ds_read_b64_tr_b16 v[220:221], v168 offset:0x1180
	v_mfma_f32_16x16x32_bf16 v[40:43], v[222:225], v[140:143], v[40:43]
	ds_read_b64_tr_b16 v[222:223], v168 offset:0x4480
	ds_read_b64_tr_b16 v[224:225], v168 offset:0x5580
	v_mfma_f32_16x16x32_bf16 v[44:47], v[226:229], v[136:139], v[44:47]
	ds_read_b64_tr_b16 v[226:227], v168 offset:0xa0
	ds_read_b64_tr_b16 v[228:229], v168 offset:0x11a0
	v_mfma_f32_16x16x32_bf16 v[44:47], v[232:235], v[140:143], v[44:47]
	ds_read_b64_tr_b16 v[232:233], v168 offset:0x44a0
	ds_read_b64_tr_b16 v[234:235], v168 offset:0x55a0
	s_waitcnt lgkmcnt(8)
	v_mfma_f32_16x16x32_bf16 v[52:55], v[236:239], v[136:139], v[52:55]
	v_mul_f32_e32 v62, v158, v62
	v_mul_f32_e32 v63, v159, v63
	v_mul_f32_e32 v60, v160, v60
	v_mul_f32_e32 v61, v161, v61
	v_mul_f32_e32 v58, v158, v58
	v_mul_f32_e32 v59, v159, v59
	v_mul_f32_e32 v56, v160, v56
	v_mul_f32_e32 v57, v161, v57
	ds_read_b64_tr_b16 v[236:237], v168 offset:0xc0
	ds_read_b64_tr_b16 v[238:239], v168 offset:0x11c0
	v_mfma_f32_16x16x32_bf16 v[52:55], v[240:243], v[140:143], v[52:55]
	ds_read_b64_tr_b16 v[240:241], v168 offset:0x44c0
	ds_read_b64_tr_b16 v[242:243], v168 offset:0x55c0
	v_mfma_f32_16x16x32_bf16 v[48:51], v[244:247], v[136:139], v[48:51]
	ds_read_b64_tr_b16 v[244:245], v168 offset:0xe0
	ds_read_b64_tr_b16 v[246:247], v168 offset:0x11e0
	v_mfma_f32_16x16x32_bf16 v[48:51], v[248:251], v[140:143], v[48:51]
	ds_read_b64_tr_b16 v[248:249], v168 offset:0x44e0
	ds_read_b64_tr_b16 v[250:251], v168 offset:0x55e0
	s_waitcnt lgkmcnt(8)
	v_mfma_f32_16x16x32_bf16 v[60:63], v[218:221], v[136:139], v[60:63]
	v_mul_f32_e32 v70, v158, v70
	v_mul_f32_e32 v71, v159, v71
	v_mul_f32_e32 v68, v160, v68
	v_mul_f32_e32 v69, v161, v69
	v_mul_f32_e32 v66, v158, v66
	v_mul_f32_e32 v67, v159, v67
	v_mul_f32_e32 v64, v160, v64
	v_mul_f32_e32 v65, v161, v65
	ds_read_b64_tr_b16 v[218:219], v168 offset:0x100
	ds_read_b64_tr_b16 v[220:221], v168 offset:0x1200
	v_mfma_f32_16x16x32_bf16 v[60:63], v[222:225], v[140:143], v[60:63]
	ds_read_b64_tr_b16 v[222:223], v168 offset:0x4500
	ds_read_b64_tr_b16 v[224:225], v168 offset:0x5600
	v_mfma_f32_16x16x32_bf16 v[56:59], v[226:229], v[136:139], v[56:59]
	ds_read_b64_tr_b16 v[226:227], v168 offset:0x120
	ds_read_b64_tr_b16 v[228:229], v168 offset:0x1220
	v_mfma_f32_16x16x32_bf16 v[56:59], v[232:235], v[140:143], v[56:59]
	ds_read_b64_tr_b16 v[232:233], v168 offset:0x4520
	ds_read_b64_tr_b16 v[234:235], v168 offset:0x5620
	s_waitcnt lgkmcnt(8)
	v_mfma_f32_16x16x32_bf16 v[68:71], v[236:239], v[136:139], v[68:71]
	v_mul_f32_e32 v78, v158, v78
	v_mul_f32_e32 v79, v159, v79
	v_mul_f32_e32 v76, v160, v76
	v_mul_f32_e32 v77, v161, v77
	v_mul_f32_e32 v74, v158, v74
	v_mul_f32_e32 v75, v159, v75
	v_mul_f32_e32 v72, v160, v72
	v_mul_f32_e32 v73, v161, v73
	ds_read_b64_tr_b16 v[236:237], v168 offset:0x140
	ds_read_b64_tr_b16 v[238:239], v168 offset:0x1240
	v_mfma_f32_16x16x32_bf16 v[68:71], v[240:243], v[140:143], v[68:71]
	ds_read_b64_tr_b16 v[240:241], v168 offset:0x4540
	ds_read_b64_tr_b16 v[242:243], v168 offset:0x5640
	v_mfma_f32_16x16x32_bf16 v[64:67], v[244:247], v[136:139], v[64:67]
	ds_read_b64_tr_b16 v[244:245], v168 offset:0x160
	ds_read_b64_tr_b16 v[246:247], v168 offset:0x1260
	v_mfma_f32_16x16x32_bf16 v[64:67], v[248:251], v[140:143], v[64:67]
	ds_read_b64_tr_b16 v[248:249], v168 offset:0x4560
	ds_read_b64_tr_b16 v[250:251], v168 offset:0x5660
	s_waitcnt lgkmcnt(8)
; #define MFMA16(a, b, c) __builtin_amdgcn_mfma_f32_16x16x32_bf16((a), (b), (c), 0, 0, 0)
; #define RT_CB() do { asm volatile("" ::: "memory"); __builtin_amdgcn_sched_barrier(0); } while (0)
; #define RT_LGKM(n) do { asm volatile("s_waitcnt lgkmcnt(" #n ")" ::: "memory"); __builtin_amdgcn_sched_barrier(0); } while (0)
; template <int FWD, class BarrierFn>
; DI void scan2_dir(const bf16_t* __restrict__ Qg, const bf16_t* __restrict__ Kg, bf16_t* Vg, bf16_t* Tg, bf16_t* TCB, float* stats, int b, int h, int sl, float lg, char* lds, const BarrierFn& gbar) {
;     ...
;             kt_load<2>(kb2, kb_tr);  RT_LGKM(8); kt_mma(st[0], st[1], ka, vz0, vz1);
;             kt_load<4>(ka, kb_tr);   RT_LGKM(8); kt_mma(st[2], st[3], kb2, vz0, vz1);
;             kt_load<6>(kb2, kb_tr);  RT_LGKM(8); kt_mma(st[4], st[5], ka, vz0, vz1);
;             kt_load<8>(ka, kb_tr);   RT_LGKM(8); kt_mma(st[6], st[7], kb2, vz0, vz1);
;             kt_load<10>(kb2, kb_tr); RT_LGKM(8); kt_mma(st[8], st[9], ka, vz0, vz1);
;             kt_load<12>(ka, kb_tr);  RT_LGKM(8); kt_mma(st[10], st[11], kb2, vz0, vz1);
;             kt_load<14>(kb2, kb_tr); RT_LGKM(8); kt_mma(st[12], st[13], ka, vz0, vz1);
;             RT_LGKM(0); kt_mma(st[14], st[15], kb2, vz0, vz1);
;         }
;         __syncthreads();
;         {
;             bf16x8 pa[4], pb[4];
; #pragma unroll
;             for (int nt = 0; nt < 4; ++nt) { pa[nt] = *(const bf16x8*)(p_rd + nt * 16 * PRS); pb[nt] = *(const bf16x8*)(p_rd + nt * 16 * PRS + 64); }
;             RT_CB();
; #pragma unroll
;             for (int nt = 0; nt < 4; ++nt) { o[nt] = MFMA16(pa[nt], vf0, o[nt]); o[nt] = MFMA16(pb[nt], vf1, o[nt]); }
;         }
; #pragma unroll
;         for (int nt = 0; nt < 4; ++nt)
; #pragma unroll
;             for (int r = 0; r < 4; ++r) stg_w[(nt * 16 + r) * S2RS] = o[nt][r];
;         __syncthreads();
;         if (step + 1 < 68) R2_WRITE();
	v_mfma_f32_16x16x32_bf16 v[76:79], v[218:221], v[136:139], v[76:79]
	v_mul_f32_e32 v86, v158, v86
	v_mul_f32_e32 v87, v159, v87
	v_mul_f32_e32 v84, v160, v84
	v_mul_f32_e32 v85, v161, v85
	v_mul_f32_e32 v82, v158, v82
	v_mul_f32_e32 v83, v159, v83
	v_mul_f32_e32 v80, v160, v80
	v_mul_f32_e32 v81, v161, v81
	ds_read_b64_tr_b16 v[218:219], v168 offset:0x180
	ds_read_b64_tr_b16 v[220:221], v168 offset:0x1280
	v_mfma_f32_16x16x32_bf16 v[76:79], v[222:225], v[140:143], v[76:79]
	ds_read_b64_tr_b16 v[222:223], v168 offset:0x4580
	ds_read_b64_tr_b16 v[224:225], v168 offset:0x5680
	v_mfma_f32_16x16x32_bf16 v[72:75], v[226:229], v[136:139], v[72:75]
	ds_read_b64_tr_b16 v[226:227], v168 offset:0x1a0
	ds_read_b64_tr_b16 v[228:229], v168 offset:0x12a0
	v_mfma_f32_16x16x32_bf16 v[72:75], v[232:235], v[140:143], v[72:75]
	ds_read_b64_tr_b16 v[232:233], v168 offset:0x45a0
	ds_read_b64_tr_b16 v[234:235], v168 offset:0x56a0
	s_waitcnt lgkmcnt(8)
	v_mfma_f32_16x16x32_bf16 v[84:87], v[236:239], v[136:139], v[84:87]
	v_mul_f32_e32 v94, v158, v94
	v_mul_f32_e32 v95, v159, v95
	v_mul_f32_e32 v92, v160, v92
	v_mul_f32_e32 v93, v161, v93
	v_mul_f32_e32 v102, v158, v102
	v_mul_f32_e32 v103, v159, v103
	v_mul_f32_e32 v100, v160, v100
	v_mul_f32_e32 v101, v161, v101
	ds_read_b64_tr_b16 v[236:237], v168 offset:0x1c0
	ds_read_b64_tr_b16 v[238:239], v168 offset:0x12c0
	v_mfma_f32_16x16x32_bf16 v[84:87], v[240:243], v[140:143], v[84:87]
	ds_read_b64_tr_b16 v[240:241], v168 offset:0x45c0
	ds_read_b64_tr_b16 v[242:243], v168 offset:0x56c0
	v_mfma_f32_16x16x32_bf16 v[80:83], v[244:247], v[136:139], v[80:83]
	ds_read_b64_tr_b16 v[244:245], v168 offset:0x1e0
	ds_read_b64_tr_b16 v[246:247], v168 offset:0x12e0
	v_mfma_f32_16x16x32_bf16 v[80:83], v[248:251], v[140:143], v[80:83]
	ds_read_b64_tr_b16 v[248:249], v168 offset:0x45e0
	ds_read_b64_tr_b16 v[250:251], v168 offset:0x56e0
	s_waitcnt lgkmcnt(8)
	v_mfma_f32_16x16x32_bf16 v[92:95], v[218:221], v[136:139], v[92:95]
	v_mul_f32_e32 v98, v158, v98
	v_mul_f32_e32 v99, v159, v99
	v_mul_f32_e32 v96, v160, v96
	v_mul_f32_e32 v97, v161, v97
	v_mul_f32_e32 v90, v158, v90
	v_mul_f32_e32 v91, v159, v91
	v_mul_f32_e32 v88, v160, v88
	v_mul_f32_e32 v89, v161, v89
	s_waitcnt lgkmcnt(0)
	v_mfma_f32_16x16x32_bf16 v[100:103], v[226:229], v[136:139], v[100:103]
	v_mfma_f32_16x16x32_bf16 v[92:95], v[222:225], v[140:143], v[92:95]
	v_mfma_f32_16x16x32_bf16 v[100:103], v[232:235], v[140:143], v[100:103]
	v_mfma_f32_16x16x32_bf16 v[96:99], v[236:239], v[136:139], v[96:99]
	s_waitcnt lgkmcnt(0)
	s_barrier
	v_mfma_f32_16x16x32_bf16 v[88:91], v[244:247], v[136:139], v[88:91]
	v_mfma_f32_16x16x32_bf16 v[96:99], v[240:243], v[140:143], v[96:99]
	v_mfma_f32_16x16x32_bf16 v[88:91], v[248:251], v[140:143], v[88:91]
	ds_read_b128 v[136:139], v217
	ds_read_b128 v[140:143], v217 offset:64
	ds_read_b128 v[218:221], v217 offset:2304
	ds_read_b128 v[222:225], v217 offset:2368
	ds_read_b128 v[226:229], v217 offset:4608
	ds_read_b128 v[232:235], v217 offset:4672
	ds_read_b128 v[236:239], v217 offset:6912
	ds_read_b128 v[240:243], v217 offset:6976
	s_waitcnt lgkmcnt(7)
	v_mfma_f32_16x16x32_bf16 v[132:135], v[136:139], v[120:123], v[132:135]
	s_andn2_b64 vcc, exec, s[0:1]
	s_waitcnt lgkmcnt(5)
	v_mfma_f32_16x16x32_bf16 v[128:131], v[218:221], v[120:123], v[128:131]
	v_mfma_f32_16x16x32_bf16 v[132:135], v[140:143], v[124:127], v[132:135]
	s_waitcnt lgkmcnt(3)
	v_mfma_f32_16x16x32_bf16 v[116:119], v[226:229], v[120:123], v[116:119]
	v_mfma_f32_16x16x32_bf16 v[128:131], v[222:225], v[124:127], v[128:131]
	s_nop 4
	ds_write2_b32 v208, v132, v133 offset1:132
	v_add_u32_e32 v132, 0x400, v208
	ds_write2_b32 v132, v134, v135 offset0:8 offset1:140
	s_waitcnt lgkmcnt(3)
	v_mfma_f32_16x16x32_bf16 v[112:115], v[236:239], v[120:123], v[112:115]
	v_add_u32_e32 v132, 0x2000, v208
	ds_write2_b32 v132, v128, v129 offset0:64 offset1:196
	v_add_u32_e32 v128, 0x2400, v208
	v_mfma_f32_16x16x32_bf16 v[116:119], v[232:235], v[124:127], v[116:119]
	ds_write2_b32 v128, v130, v131 offset0:72 offset1:204
	v_add_u32_e32 v128, 0x4200, v208
	s_waitcnt lgkmcnt(4)
	v_mfma_f32_16x16x32_bf16 v[112:115], v[240:243], v[124:127], v[112:115]
	s_nop 3
	ds_write2_b32 v128, v116, v117 offset1:132
	v_add_u32_e32 v116, 0x4600, v208
	ds_write2_b32 v116, v118, v119 offset0:8 offset1:140
	v_add_u32_e32 v116, 0x6200, v208
	ds_write2_b32 v116, v112, v113 offset0:64 offset1:196
	v_add_u32_e32 v112, 0x6600, v208
	ds_write2_b32 v112, v114, v115 offset0:72 offset1:204
	s_waitcnt lgkmcnt(0)
	s_barrier
	s_cbranch_vccnz .LBB0_364
	s_waitcnt vmcnt(9)
	ds_write_b128 v200, v[0:3]
	s_waitcnt vmcnt(8)
	ds_write_b128 v201, v[4:7] offset:33792
	s_waitcnt vmcnt(7)
	ds_write_b128 v202, v[8:11]
	s_waitcnt vmcnt(6)
	ds_write_b128 v203, v[12:15] offset:33792
	s_waitcnt vmcnt(5)
	ds_write_b128 v204, v[16:19]
	s_waitcnt vmcnt(4)
	ds_write_b128 v205, v[20:23] offset:33792
	s_waitcnt vmcnt(3)
	ds_write_b128 v206, v[24:27]
	s_waitcnt vmcnt(2)
	ds_write_b128 v207, v[28:31] offset:33792
	s_waitcnt vmcnt(1)
	ds_write_b128 v210, v[32:35]
	s_waitcnt vmcnt(0)
	ds_write_b128 v211, v[36:39]

; DI unsigned cvt_pk_bf16(float lo, float hi) { unsigned r; asm volatile("v_cvt_pk_bf16_f32 %0, %1, %2" : "=v"(r) : "v"(lo), "v"(hi)); return r; }
; #define RT_LGKM(n) do { asm volatile("s_waitcnt lgkmcnt(" #n ")" ::: "memory"); __builtin_amdgcn_sched_barrier(0); } while (0)
; template <int FWD, class BarrierFn>
; DI void scan2_dir(const bf16_t* __restrict__ Qg, const bf16_t* __restrict__ Kg, bf16_t* Vg, bf16_t* Tg, bf16_t* TCB, float* stats, int b, int h, int sl, float lg, char* lds, const BarrierFn& gbar) {
;     ...
;             f32x4 s0 = {0.f, 0.f, 0.f, 0.f}, s1 = {0.f, 0.f, 0.f, 0.f};
;             bf16x8 ak[2], aq0[2], aq1[2], bk[2], bq0[2], bq1[2];
;     ...
;             ST_LOAD(ak, aq0, aq1, 0); ST_LOAD(bk, bq0, bq1, 2);
;             ST_MMA(ak, aq0, aq1); ST_LOAD(ak, aq0, aq1, 4);
;             ST_MMA(bk, bq0, bq1); ST_LOAD(bk, bq0, bq1, 6);
;             ST_MMA(ak, aq0, aq1); ST_MMA(bk, bq0, bq1);
;     ...
;             const int n0 = 16 * qt0 + c, n1 = n0 + 16, mb = 16 * kt + 4 * g;
;             float p0[4], p1[4];
; #pragma unroll
;             for (int jj = 0; jj < 4; ++jj) { const int m = mb + jj; const float wmv = wm[jj];
;                 const bool k0 = FWD ? (m <= n0) : (m > n0), k1 = FWD ? (m <= n1) : (m > n1);
;                 p0[jj] = k0 ? s0[jj] * wmv : 0.f; p1[jj] = k1 ? s1[jj] * wmv : 0.f; }
;             u32x2 w0 = {cvt_pk_bf16(p0[0], p0[1]), cvt_pk_bf16(p0[2], p0[3])}, w1 = {cvt_pk_bf16(p1[0], p1[1]), cvt_pk_bf16(p1[2], p1[3])};
;             *(u32x2*)(lds + P2_OFF + n0 * PRS + mb * 2) = w0; *(u32x2*)(lds + P2_OFF + n1 * PRS + mb * 2) = w1;
;         }
;         f32x4 o[4];
; #pragma unroll
;         for (int nt = 0; nt < 4; ++nt) o[nt] = (f32x4){0.f, 0.f, 0.f, 0.f};
;         {
;             bf16x8 qa[4], qb[4];
;     ...
;             qs_load<0>(qa, qs_b); qs_load<1>(qb, qs_b);
;             RT_LGKM(8); QS_MMA(qa, 0); qs_load<2>(qa, qs_b);
;             RT_LGKM(8); QS_MMA(qb, 1); qs_load<3>(qb, qs_b);
;             RT_LGKM(8); QS_MMA(qa, 2); qs_load<4>(qa, qs_b);
;             RT_LGKM(8); QS_MMA(qb, 3); qs_load<5>(qb, qs_b);
;             RT_LGKM(8); QS_MMA(qa, 4); qs_load<6>(qa, qs_b);
;             RT_LGKM(8); QS_MMA(qb, 5); qs_load<7>(qb, qs_b);
;             RT_LGKM(8); QS_MMA(qa, 6);
;             RT_LGKM(0); QS_MMA(qb, 7);
.LBB0_443:
	ds_read_b128 v[112:115], v212 offset:33792
	ds_read_b128 v[116:119], v212 offset:33856
	ds_read_b128 v[120:123], v213
	ds_read_b128 v[124:127], v213 offset:64
	ds_read_b128 v[128:131], v213 offset:8448
	ds_read_b128 v[132:135], v213 offset:8512
	ds_read_b128 v[136:139], v212 offset:33920
	ds_read_b128 v[140:143], v212 offset:33984
	ds_read_b128 v[216:219], v213 offset:128
	ds_read_b128 v[220:223], v213 offset:192
	ds_read_b128 v[224:227], v213 offset:8576
	ds_read_b128 v[232:235], v213 offset:8640
	s_waitcnt lgkmcnt(9)
	v_mfma_f32_16x16x32_bf16 v[120:123], v[112:115], v[120:123], 0
	s_waitcnt lgkmcnt(7)
	v_mfma_f32_16x16x32_bf16 v[112:115], v[112:115], v[128:131], 0
	ds_read_b128 v[128:131], v212 offset:34048
	ds_read_b128 v[236:239], v212 offset:34112
	ds_read_b128 v[240:243], v213 offset:256
	ds_read_b128 v[244:247], v213 offset:320
	v_mfma_f32_16x16x32_bf16 v[120:123], v[116:119], v[124:127], v[120:123]
	ds_read_b128 v[124:127], v213 offset:8704
	ds_read_b128 v[248:251], v213 offset:8768
	s_waitcnt lgkmcnt(12)
	v_mfma_f32_16x16x32_bf16 v[112:115], v[116:119], v[132:135], v[112:115]
	s_waitcnt lgkmcnt(9)
	v_mfma_f32_16x16x32_bf16 v[116:119], v[136:139], v[216:219], v[120:123]
	s_waitcnt lgkmcnt(7)
	v_mfma_f32_16x16x32_bf16 v[112:115], v[136:139], v[224:227], v[112:115]
	s_nop 0
	ds_read_b128 v[120:123], v212 offset:34176
	ds_read_b128 v[132:135], v212 offset:34240
	ds_read_b128 v[136:139], v213 offset:384
	ds_read_b128 v[216:219], v213 offset:448
	v_mfma_f32_16x16x32_bf16 v[116:119], v[140:143], v[220:223], v[116:119]
	ds_read_b128 v[220:223], v213 offset:8832
	ds_read_b128 v[224:227], v213 offset:8896
	s_waitcnt lgkmcnt(12)
	v_mfma_f32_16x16x32_bf16 v[112:115], v[140:143], v[232:235], v[112:115]
	s_waitcnt lgkmcnt(9)
	v_mfma_f32_16x16x32_bf16 v[116:119], v[128:131], v[240:243], v[116:119]
	s_waitcnt lgkmcnt(7)
	v_mfma_f32_16x16x32_bf16 v[112:115], v[128:131], v[124:127], v[112:115]
	v_mfma_f32_16x16x32_bf16 v[116:119], v[236:239], v[244:247], v[116:119]
	s_waitcnt lgkmcnt(6)
	v_mfma_f32_16x16x32_bf16 v[112:115], v[236:239], v[248:251], v[112:115]
	s_waitcnt lgkmcnt(3)
	v_mfma_f32_16x16x32_bf16 v[116:119], v[120:123], v[136:139], v[116:119]
	s_waitcnt lgkmcnt(1)
	v_mfma_f32_16x16x32_bf16 v[112:115], v[120:123], v[220:223], v[112:115]
	v_mfma_f32_16x16x32_bf16 v[116:119], v[132:135], v[216:219], v[116:119]
	s_waitcnt lgkmcnt(0)
	v_mfma_f32_16x16x32_bf16 v[112:115], v[132:135], v[224:227], v[112:115]
	s_nop 7
	v_mul_f32_e32 v112, v167, v112
	v_mul_f32_e32 v113, v168, v113
	v_mul_f32_e32 v116, v167, v116
	v_cndmask_b32_e64 v120, 0, v112, s[8:9]
	v_mul_f32_e32 v112, v168, v117
	v_cndmask_b32_e64 v117, v113, 0, s[12:13]
	v_mul_f32_e32 v113, v169, v118
	v_mul_f32_e32 v114, v169, v114
	v_cndmask_b32_e64 v116, 0, v116, s[6:7]
	v_cndmask_b32_e64 v112, v112, 0, s[10:11]
	v_cndmask_b32_e64 v113, 0, v113, s[14:15]
	v_cndmask_b32_e64 v118, 0, v114, s[16:17]
	v_mul_f32_e32 v114, v170, v119
	v_mul_f32_e32 v115, v170, v115
	v_cndmask_b32_e64 v114, 0, v114, s[18:19]
	v_cndmask_b32_e64 v115, 0, v115, s[20:21]
	v_cvt_pk_bf16_f32 v112, v116, v112
	v_cvt_pk_bf16_f32 v113, v113, v114
	v_add_u32_e32 v116, v210, v211
	v_cvt_pk_bf16_f32 v114, v120, v117
	v_cvt_pk_bf16_f32 v115, v118, v115
	ds_write_b64 v116, v[112:113]
	ds_write_b64 v214, v[114:115]
	ds_read_b64 v[112:113], v197 offset:0
	ds_read_b64 v[114:115], v197 offset:32
	ds_read_b64 v[116:117], v197 offset:0x2100
	ds_read_b64 v[118:119], v197 offset:0x2120
	ds_read_b64 v[120:121], v197 offset:0x4200
	ds_read_b64 v[122:123], v197 offset:0x4220
	ds_read_b64 v[124:125], v197 offset:0x6300
	ds_read_b64 v[126:127], v197 offset:0x6320
	ds_read_b64 v[128:129], v197 offset:64
	ds_read_b64 v[130:131], v197 offset:0x60
	ds_read_b64 v[132:133], v197 offset:0x2140
	ds_read_b64 v[134:135], v197 offset:0x2160
	ds_read_b64 v[136:137], v197 offset:0x4240
	ds_read_b64 v[138:139], v197 offset:0x4260
	ds_read_b64 v[140:141], v197 offset:0x6340
	ds_read_b64 v[142:143], v197 offset:0x6360
	s_waitcnt lgkmcnt(8)
	v_cvt_pk_bf16_f32 v216, v40, v41
	v_cvt_pk_bf16_f32 v217, v42, v43
	v_cvt_pk_bf16_f32 v218, v44, v45
	v_cvt_pk_bf16_f32 v219, v46, v47
	s_nop 0
	v_mfma_f32_16x16x32_bf16 v[112:115], v[112:115], v[216:219], 0
	v_mfma_f32_16x16x32_bf16 v[116:119], v[116:119], v[216:219], 0
	v_mfma_f32_16x16x32_bf16 v[120:123], v[120:123], v[216:219], 0
	v_mfma_f32_16x16x32_bf16 v[124:127], v[124:127], v[216:219], 0
	ds_read_b64 v[216:217], v197 offset:0x80
	ds_read_b64 v[218:219], v197 offset:0xa0
	ds_read_b64 v[220:221], v197 offset:0x2180
	ds_read_b64 v[222:223], v197 offset:0x21a0
	ds_read_b64 v[224:225], v197 offset:0x4280
	ds_read_b64 v[226:227], v197 offset:0x42a0
	ds_read_b64 v[232:233], v197 offset:0x6380
	ds_read_b64 v[234:235], v197 offset:0x63a0
	s_waitcnt lgkmcnt(8)
	v_cvt_pk_bf16_f32 v236, v52, v53
	v_cvt_pk_bf16_f32 v237, v54, v55
	v_cvt_pk_bf16_f32 v238, v48, v49
	v_cvt_pk_bf16_f32 v239, v50, v51
	s_nop 0
	v_mfma_f32_16x16x32_bf16 v[112:115], v[128:131], v[236:239], v[112:115]
	ds_read_b64 v[128:129], v197 offset:0xc0
	ds_read_b64 v[130:131], v197 offset:0xe0
	v_mfma_f32_16x16x32_bf16 v[116:119], v[132:135], v[236:239], v[116:119]
	ds_read_b64 v[132:133], v197 offset:0x21c0
	ds_read_b64 v[134:135], v197 offset:0x21e0
	v_mfma_f32_16x16x32_bf16 v[120:123], v[136:139], v[236:239], v[120:123]
	ds_read_b64 v[136:137], v197 offset:0x42c0
	ds_read_b64 v[138:139], v197 offset:0x42e0
	v_mfma_f32_16x16x32_bf16 v[124:127], v[140:143], v[236:239], v[124:127]
	ds_read_b64 v[140:141], v197 offset:0x63c0
	ds_read_b64 v[142:143], v197 offset:0x63e0
	s_waitcnt lgkmcnt(8)
; template <int OFF> DI s16x4 tr_rd(unsigned addr) { s16x4 r; asm volatile("ds_read_b64_tr_b16 %0, %1 offset:%2" : "=&v"(r) : "v"(addr), "i"(OFF) : "memory"); return r; }
; #define RT_LGKM(n) do { asm volatile("s_waitcnt lgkmcnt(" #n ")" ::: "memory"); __builtin_amdgcn_sched_barrier(0); } while (0)
; template <int FWD, class BarrierFn>
; DI void scan2_dir(const bf16_t* __restrict__ Qg, const bf16_t* __restrict__ Kg, bf16_t* Vg, bf16_t* Tg, bf16_t* TCB, float* stats, int b, int h, int sl, float lg, char* lds, const BarrierFn& gbar) {
;     ...
;             qs_load<0>(qa, qs_b); qs_load<1>(qb, qs_b);
;             RT_LGKM(8); QS_MMA(qa, 0); qs_load<2>(qa, qs_b);
;             RT_LGKM(8); QS_MMA(qb, 1); qs_load<3>(qb, qs_b);
;             RT_LGKM(8); QS_MMA(qa, 2); qs_load<4>(qa, qs_b);
;             RT_LGKM(8); QS_MMA(qb, 3); qs_load<5>(qb, qs_b);
;             RT_LGKM(8); QS_MMA(qa, 4); qs_load<6>(qa, qs_b);
;             RT_LGKM(8); QS_MMA(qb, 5); qs_load<7>(qb, qs_b);
;             RT_LGKM(8); QS_MMA(qa, 6);
;             RT_LGKM(0); QS_MMA(qb, 7);
;     ...
;         }
;         bf16x8 vf0, vf1;
;         {
;             const s16x4 l0 = tr_rd<0>(vb_tr), h0 = tr_rd<8 * V2RS>(vb_tr), l1 = tr_rd<32 * V2RS>(vb_tr), h1 = tr_rd<40 * V2RS>(vb_tr);
;             KT8 ka, kb2;
;             kt_load<0>(ka, kb_tr);
	v_cvt_pk_bf16_f32 v236, v60, v61
	v_cvt_pk_bf16_f32 v237, v62, v63
	v_cvt_pk_bf16_f32 v238, v56, v57
	v_cvt_pk_bf16_f32 v239, v58, v59
	s_nop 0
	v_mfma_f32_16x16x32_bf16 v[112:115], v[216:219], v[236:239], v[112:115]
	ds_read_b64 v[216:217], v197 offset:0x100
	ds_read_b64 v[218:219], v197 offset:0x120
	v_mfma_f32_16x16x32_bf16 v[116:119], v[220:223], v[236:239], v[116:119]
	ds_read_b64 v[220:221], v197 offset:0x2200
	ds_read_b64 v[222:223], v197 offset:0x2220
	v_mfma_f32_16x16x32_bf16 v[120:123], v[224:227], v[236:239], v[120:123]
	ds_read_b64 v[224:225], v197 offset:0x4300
	ds_read_b64 v[226:227], v197 offset:0x4320
	v_mfma_f32_16x16x32_bf16 v[124:127], v[232:235], v[236:239], v[124:127]
	ds_read_b64 v[232:233], v197 offset:0x6400
	ds_read_b64 v[234:235], v197 offset:0x6420
	s_waitcnt lgkmcnt(8)
	v_cvt_pk_bf16_f32 v236, v68, v69
	v_cvt_pk_bf16_f32 v237, v70, v71
	v_cvt_pk_bf16_f32 v238, v64, v65
	v_cvt_pk_bf16_f32 v239, v66, v67
	s_nop 0
	v_mfma_f32_16x16x32_bf16 v[112:115], v[128:131], v[236:239], v[112:115]
	ds_read_b64 v[128:129], v197 offset:0x140
	ds_read_b64 v[130:131], v197 offset:0x160
	v_mfma_f32_16x16x32_bf16 v[116:119], v[132:135], v[236:239], v[116:119]
	ds_read_b64 v[132:133], v197 offset:0x2240
	ds_read_b64 v[134:135], v197 offset:0x2260
	v_mfma_f32_16x16x32_bf16 v[120:123], v[136:139], v[236:239], v[120:123]
	ds_read_b64 v[136:137], v197 offset:0x4340
	ds_read_b64 v[138:139], v197 offset:0x4360
	v_mfma_f32_16x16x32_bf16 v[124:127], v[140:143], v[236:239], v[124:127]
	ds_read_b64 v[140:141], v197 offset:0x6440
	ds_read_b64 v[142:143], v197 offset:0x6460
	s_waitcnt lgkmcnt(8)
	v_cvt_pk_bf16_f32 v236, v76, v77
	v_cvt_pk_bf16_f32 v237, v78, v79
	v_cvt_pk_bf16_f32 v238, v72, v73
	v_cvt_pk_bf16_f32 v239, v74, v75
	s_nop 0
	v_mfma_f32_16x16x32_bf16 v[112:115], v[216:219], v[236:239], v[112:115]
	ds_read_b64 v[216:217], v197 offset:0x180
	ds_read_b64 v[218:219], v197 offset:0x1a0
	v_mfma_f32_16x16x32_bf16 v[116:119], v[220:223], v[236:239], v[116:119]
	ds_read_b64 v[220:221], v197 offset:0x2280
	ds_read_b64 v[222:223], v197 offset:0x22a0
	v_mfma_f32_16x16x32_bf16 v[120:123], v[224:227], v[236:239], v[120:123]
	ds_read_b64 v[224:225], v197 offset:0x4380
	ds_read_b64 v[226:227], v197 offset:0x43a0
	v_mfma_f32_16x16x32_bf16 v[124:127], v[232:235], v[236:239], v[124:127]
	ds_read_b64 v[232:233], v197 offset:0x6480
	ds_read_b64 v[234:235], v197 offset:0x64a0
	s_waitcnt lgkmcnt(8)
	v_cvt_pk_bf16_f32 v236, v84, v85
	v_cvt_pk_bf16_f32 v237, v86, v87
	v_cvt_pk_bf16_f32 v238, v80, v81
	v_cvt_pk_bf16_f32 v239, v82, v83
	s_nop 0
	v_mfma_f32_16x16x32_bf16 v[112:115], v[128:131], v[236:239], v[112:115]
	ds_read_b64 v[128:129], v197 offset:0x1c0
	ds_read_b64 v[130:131], v197 offset:0x1e0
	v_mfma_f32_16x16x32_bf16 v[120:123], v[136:139], v[236:239], v[120:123]
	ds_read_b64 v[136:137], v197 offset:0x22c0
	ds_read_b64 v[138:139], v197 offset:0x22e0
	v_mfma_f32_16x16x32_bf16 v[124:127], v[140:143], v[236:239], v[124:127]
	ds_read_b64 v[140:141], v197 offset:0x43c0
	ds_read_b64 v[142:143], v197 offset:0x43e0
	v_mfma_f32_16x16x32_bf16 v[116:119], v[132:135], v[236:239], v[116:119]
	ds_read_b64 v[236:237], v197 offset:0x64c0
	ds_read_b64 v[238:239], v197 offset:0x64e0
	s_waitcnt lgkmcnt(8)
	v_cvt_pk_bf16_f32 v132, v92, v93
	v_cvt_pk_bf16_f32 v133, v94, v95
	v_cvt_pk_bf16_f32 v134, v100, v101
	v_cvt_pk_bf16_f32 v135, v102, v103
	s_waitcnt lgkmcnt(0)
	s_nop 0
	v_mfma_f32_16x16x32_bf16 v[112:115], v[216:219], v[132:135], v[112:115]
	v_mfma_f32_16x16x32_bf16 v[116:119], v[220:223], v[132:135], v[116:119]
	v_mfma_f32_16x16x32_bf16 v[120:123], v[224:227], v[132:135], v[120:123]
	v_mfma_f32_16x16x32_bf16 v[124:127], v[232:235], v[132:135], v[124:127]
	v_cvt_pk_bf16_f32 v216, v96, v97
	v_cvt_pk_bf16_f32 v217, v98, v99
	v_cvt_pk_bf16_f32 v218, v88, v89
	v_cvt_pk_bf16_f32 v219, v90, v91
	s_nop 0
	v_mfma_f32_16x16x32_bf16 v[132:135], v[128:131], v[216:219], v[112:115]
	v_mfma_f32_16x16x32_bf16 v[128:131], v[136:139], v[216:219], v[116:119]
	v_mfma_f32_16x16x32_bf16 v[116:119], v[140:143], v[216:219], v[120:123]
	ds_read_b64_tr_b16 v[120:121], v196 offset:0
	ds_read_b64_tr_b16 v[122:123], v196 offset:0x900
	v_mfma_f32_16x16x32_bf16 v[112:115], v[236:239], v[216:219], v[124:127]
	ds_read_b64_tr_b16 v[124:125], v196 offset:0x2400
	ds_read_b64_tr_b16 v[126:127], v196 offset:0x2d00
	ds_read_b64_tr_b16 v[216:217], v166 offset:0
	ds_read_b64_tr_b16 v[218:219], v166 offset:0x1100
	ds_read_b64_tr_b16 v[220:221], v166 offset:0x4400
	ds_read_b64_tr_b16 v[222:223], v166 offset:0x5500
	ds_read_b64_tr_b16 v[224:225], v166 offset:32
	ds_read_b64_tr_b16 v[226:227], v166 offset:0x1120
	ds_read_b64_tr_b16 v[232:233], v166 offset:0x4420
	ds_read_b64_tr_b16 v[234:235], v166 offset:0x5520
	s_waitcnt lgkmcnt(8)
; DI unsigned cvt_pk_bf16(float lo, float hi) { unsigned r; asm volatile("v_cvt_pk_bf16_f32 %0, %1, %2" : "=v"(r) : "v"(lo), "v"(hi)); return r; }
; DI float bf2f(bf16_t b) { return __uint_as_float(((unsigned)b) << 16); }
; template <int OFF> DI s16x4 tr_rd(unsigned addr) { s16x4 r; asm volatile("ds_read_b64_tr_b16 %0, %1 offset:%2" : "=&v"(r) : "v"(addr), "i"(OFF) : "memory"); return r; }
; DI bf16x8 cat(s16x4 l, s16x4 h) { return (bf16x8){l[0], l[1], l[2], l[3], h[0], h[1], h[2], h[3]}; }
; template <int FWD, class BarrierFn>
; DI void scan2_dir(const bf16_t* __restrict__ Qg, const bf16_t* __restrict__ Kg, bf16_t* Vg, bf16_t* Tg, bf16_t* TCB, float* stats, int b, int h, int sl, float lg, char* lds, const BarrierFn& gbar) {
;     ...
;             const s16x4 l0 = tr_rd<0>(vb_tr), h0 = tr_rd<8 * V2RS>(vb_tr), l1 = tr_rd<32 * V2RS>(vb_tr), h1 = tr_rd<40 * V2RS>(vb_tr);
;             KT8 ka, kb2;
;             kt_load<0>(ka, kb_tr);
;             RT_LGKM(8);
;             vf0 = cat(l0, h0); vf1 = cat(l1, h1);
;             bf16x8 vz0, vz1;
;             {
;                 float f[8];
; #pragma unroll
;                 for (int jj = 0; jj < 8; ++jj) f[jj] = bf2f((bf16_t)vf0[jj]) * zt0[jj];
;                 u32x4 w = {cvt_pk_bf16(f[0], f[1]), cvt_pk_bf16(f[2], f[3]), cvt_pk_bf16(f[4], f[5]), cvt_pk_bf16(f[6], f[7])};
;                 vz0 = *reinterpret_cast<bf16x8*>(&w);
; #pragma unroll
;                 for (int jj = 0; jj < 8; ++jj) f[jj] = bf2f((bf16_t)vf1[jj]) * zt1[jj];
;                 u32x4 w2 = {cvt_pk_bf16(f[0], f[1]), cvt_pk_bf16(f[2], f[3]), cvt_pk_bf16(f[4], f[5]), cvt_pk_bf16(f[6], f[7])};
;                 vz1 = *reinterpret_cast<bf16x8*>(&w2);
;             }
; #pragma unroll
;             for (int t = 0; t < 16; ++t) st[t] = st[t] * gC;
;             kt_load<2>(kb2, kb_tr);  RT_LGKM(8); kt_mma(st[0], st[1], ka, vz0, vz1);
;             kt_load<4>(ka, kb_tr);   RT_LGKM(8); kt_mma(st[2], st[3], kb2, vz0, vz1);
;             kt_load<6>(kb2, kb_tr);  RT_LGKM(8); kt_mma(st[4], st[5], ka, vz0, vz1);
;             kt_load<8>(ka, kb_tr);   RT_LGKM(8); kt_mma(st[6], st[7], kb2, vz0, vz1);
;             kt_load<10>(kb2, kb_tr); RT_LGKM(8); kt_mma(st[8], st[9], ka, vz0, vz1);
;             kt_load<12>(ka, kb_tr);  RT_LGKM(8); kt_mma(st[10], st[11], kb2, vz0, vz1);
;             kt_load<14>(kb2, kb_tr); RT_LGKM(8); kt_mma(st[12], st[13], ka, vz0, vz1);
	s_nop 1
	v_lshlrev_b32_e32 v136, 16, v120
	v_and_b32_e32 v137, 0xffff0000, v120
	v_lshlrev_b32_e32 v138, 16, v121
	v_and_b32_e32 v139, 0xffff0000, v121
	v_lshlrev_b32_e32 v140, 16, v122
	v_and_b32_e32 v141, 0xffff0000, v122
	v_lshlrev_b32_e32 v142, 16, v123
	v_and_b32_e32 v143, 0xffff0000, v123
	v_mul_f32_e32 v136, v171, v136
	v_mul_f32_e32 v137, v173, v137
	v_mul_f32_e32 v138, v175, v138
	v_mul_f32_e32 v139, v177, v139
	v_mul_f32_e32 v140, v179, v140
	v_mul_f32_e32 v141, v185, v141
	v_mul_f32_e32 v142, v187, v142
	v_mul_f32_e32 v143, v189, v143
	v_cvt_pk_bf16_f32 v136, v136, v137
	v_cvt_pk_bf16_f32 v137, v138, v139
	v_cvt_pk_bf16_f32 v138, v140, v141
	v_cvt_pk_bf16_f32 v139, v142, v143
	v_lshlrev_b32_e32 v140, 16, v124
	v_and_b32_e32 v141, 0xffff0000, v124
	v_lshlrev_b32_e32 v142, 16, v125
	v_and_b32_e32 v143, 0xffff0000, v125
	v_mul_f32_e32 v140, v172, v140
	v_mul_f32_e32 v141, v174, v141
	v_mul_f32_e32 v142, v176, v142
	v_mul_f32_e32 v143, v178, v143
	v_lshlrev_b32_e32 v153, 16, v126
	v_and_b32_e32 v228, 0xffff0000, v126
	v_lshlrev_b32_e32 v229, 16, v127
	v_and_b32_e32 v231, 0xffff0000, v127
	v_mul_f32_e32 v153, v184, v153
	v_mul_f32_e32 v228, v186, v228
	v_mul_f32_e32 v229, v188, v229
	v_mul_f32_e32 v231, v195, v231
	v_cvt_pk_bf16_f32 v140, v140, v141
	v_cvt_pk_bf16_f32 v141, v142, v143
	v_cvt_pk_bf16_f32 v142, v153, v228
	v_cvt_pk_bf16_f32 v143, v229, v231
	ds_read_b64_tr_b16 v[236:237], v166 offset:64
	ds_read_b64_tr_b16 v[238:239], v166 offset:0x1140
	ds_read_b64_tr_b16 v[240:241], v166 offset:0x4440
	ds_read_b64_tr_b16 v[242:243], v166 offset:0x5540
	ds_read_b64_tr_b16 v[244:245], v166 offset:0x60
	ds_read_b64_tr_b16 v[246:247], v166 offset:0x1160
	ds_read_b64_tr_b16 v[248:249], v166 offset:0x4460
	ds_read_b64_tr_b16 v[250:251], v166 offset:0x5560
	s_waitcnt lgkmcnt(8)
	v_mov_b32_e32 v153, v152
	v_mul_f32_e32 v42, v152, v42
	v_mul_f32_e32 v43, v153, v43
	v_mul_f32_e32 v40, v158, v40
	v_mul_f32_e32 v41, v159, v41
	v_mul_f32_e32 v46, v152, v46
	v_mul_f32_e32 v47, v153, v47
	v_mul_f32_e32 v44, v158, v44
	v_mul_f32_e32 v45, v159, v45
	v_mfma_f32_16x16x32_bf16 v[40:43], v[216:219], v[136:139], v[40:43]
	v_mul_f32_e32 v54, v152, v54
	v_mul_f32_e32 v55, v153, v55
	v_mul_f32_e32 v52, v158, v52
	v_mul_f32_e32 v53, v159, v53
	v_mul_f32_e32 v50, v152, v50
	v_mul_f32_e32 v51, v153, v51
	v_mul_f32_e32 v48, v158, v48
	v_mul_f32_e32 v49, v159, v49
	ds_read_b64_tr_b16 v[216:217], v166 offset:0x80
	ds_read_b64_tr_b16 v[218:219], v166 offset:0x1180
	v_mfma_f32_16x16x32_bf16 v[40:43], v[220:223], v[140:143], v[40:43]
	ds_read_b64_tr_b16 v[220:221], v166 offset:0x4480
	ds_read_b64_tr_b16 v[222:223], v166 offset:0x5580
	v_mfma_f32_16x16x32_bf16 v[44:47], v[224:227], v[136:139], v[44:47]
	ds_read_b64_tr_b16 v[224:225], v166 offset:0xa0
	ds_read_b64_tr_b16 v[226:227], v166 offset:0x11a0
	v_mfma_f32_16x16x32_bf16 v[44:47], v[232:235], v[140:143], v[44:47]
	ds_read_b64_tr_b16 v[232:233], v166 offset:0x44a0
	ds_read_b64_tr_b16 v[234:235], v166 offset:0x55a0
	s_waitcnt lgkmcnt(8)
	v_mfma_f32_16x16x32_bf16 v[52:55], v[236:239], v[136:139], v[52:55]
	v_mul_f32_e32 v62, v152, v62
	v_mul_f32_e32 v63, v153, v63
	v_mul_f32_e32 v60, v158, v60
	v_mul_f32_e32 v61, v159, v61
	v_mul_f32_e32 v58, v152, v58
	v_mul_f32_e32 v59, v153, v59
	v_mul_f32_e32 v56, v158, v56
	v_mul_f32_e32 v57, v159, v57
	ds_read_b64_tr_b16 v[236:237], v166 offset:0xc0
	ds_read_b64_tr_b16 v[238:239], v166 offset:0x11c0
	v_mfma_f32_16x16x32_bf16 v[52:55], v[240:243], v[140:143], v[52:55]
	ds_read_b64_tr_b16 v[240:241], v166 offset:0x44c0
	ds_read_b64_tr_b16 v[242:243], v166 offset:0x55c0
	v_mfma_f32_16x16x32_bf16 v[48:51], v[244:247], v[136:139], v[48:51]
	ds_read_b64_tr_b16 v[244:245], v166 offset:0xe0
	ds_read_b64_tr_b16 v[246:247], v166 offset:0x11e0
	v_mfma_f32_16x16x32_bf16 v[48:51], v[248:251], v[140:143], v[48:51]
	ds_read_b64_tr_b16 v[248:249], v166 offset:0x44e0
	ds_read_b64_tr_b16 v[250:251], v166 offset:0x55e0
	s_waitcnt lgkmcnt(8)
	v_mfma_f32_16x16x32_bf16 v[60:63], v[216:219], v[136:139], v[60:63]
	v_mul_f32_e32 v70, v152, v70
	v_mul_f32_e32 v71, v153, v71
	v_mul_f32_e32 v68, v158, v68
	v_mul_f32_e32 v69, v159, v69
	v_mul_f32_e32 v66, v152, v66
	v_mul_f32_e32 v67, v153, v67
	v_mul_f32_e32 v64, v158, v64
	v_mul_f32_e32 v65, v159, v65
	ds_read_b64_tr_b16 v[216:217], v166 offset:0x100
	ds_read_b64_tr_b16 v[218:219], v166 offset:0x1200
	v_mfma_f32_16x16x32_bf16 v[60:63], v[220:223], v[140:143], v[60:63]
	ds_read_b64_tr_b16 v[220:221], v166 offset:0x4500
	ds_read_b64_tr_b16 v[222:223], v166 offset:0x5600
	v_mfma_f32_16x16x32_bf16 v[56:59], v[224:227], v[136:139], v[56:59]
	ds_read_b64_tr_b16 v[224:225], v166 offset:0x120
	ds_read_b64_tr_b16 v[226:227], v166 offset:0x1220
	v_mfma_f32_16x16x32_bf16 v[56:59], v[232:235], v[140:143], v[56:59]
	ds_read_b64_tr_b16 v[232:233], v166 offset:0x4520
	ds_read_b64_tr_b16 v[234:235], v166 offset:0x5620
	s_waitcnt lgkmcnt(8)
	v_mfma_f32_16x16x32_bf16 v[68:71], v[236:239], v[136:139], v[68:71]
	v_mul_f32_e32 v78, v152, v78
	v_mul_f32_e32 v79, v153, v79
	v_mul_f32_e32 v76, v158, v76
	v_mul_f32_e32 v77, v159, v77
	v_mul_f32_e32 v74, v152, v74
	v_mul_f32_e32 v75, v153, v75
	v_mul_f32_e32 v72, v158, v72
	v_mul_f32_e32 v73, v159, v73
	ds_read_b64_tr_b16 v[236:237], v166 offset:0x140
	ds_read_b64_tr_b16 v[238:239], v166 offset:0x1240
	v_mfma_f32_16x16x32_bf16 v[68:71], v[240:243], v[140:143], v[68:71]
	ds_read_b64_tr_b16 v[240:241], v166 offset:0x4540
	ds_read_b64_tr_b16 v[242:243], v166 offset:0x5640
	v_mfma_f32_16x16x32_bf16 v[64:67], v[244:247], v[136:139], v[64:67]
	ds_read_b64_tr_b16 v[244:245], v166 offset:0x160
	ds_read_b64_tr_b16 v[246:247], v166 offset:0x1260
	v_mfma_f32_16x16x32_bf16 v[64:67], v[248:251], v[140:143], v[64:67]
	ds_read_b64_tr_b16 v[248:249], v166 offset:0x4560
	ds_read_b64_tr_b16 v[250:251], v166 offset:0x5660
	s_waitcnt lgkmcnt(8)
; #define MFMA16(a, b, c) __builtin_amdgcn_mfma_f32_16x16x32_bf16((a), (b), (c), 0, 0, 0)
; #define RT_CB() do { asm volatile("" ::: "memory"); __builtin_amdgcn_sched_barrier(0); } while (0)
; #define RT_LGKM(n) do { asm volatile("s_waitcnt lgkmcnt(" #n ")" ::: "memory"); __builtin_amdgcn_sched_barrier(0); } while (0)
; template <int FWD, class BarrierFn>
; DI void scan2_dir(const bf16_t* __restrict__ Qg, const bf16_t* __restrict__ Kg, bf16_t* Vg, bf16_t* Tg, bf16_t* TCB, float* stats, int b, int h, int sl, float lg, char* lds, const BarrierFn& gbar) {
;     ...
;             kt_load<2>(kb2, kb_tr);  RT_LGKM(8); kt_mma(st[0], st[1], ka, vz0, vz1);
;             kt_load<4>(ka, kb_tr);   RT_LGKM(8); kt_mma(st[2], st[3], kb2, vz0, vz1);
;             kt_load<6>(kb2, kb_tr);  RT_LGKM(8); kt_mma(st[4], st[5], ka, vz0, vz1);
;             kt_load<8>(ka, kb_tr);   RT_LGKM(8); kt_mma(st[6], st[7], kb2, vz0, vz1);
;             kt_load<10>(kb2, kb_tr); RT_LGKM(8); kt_mma(st[8], st[9], ka, vz0, vz1);
;             kt_load<12>(ka, kb_tr);  RT_LGKM(8); kt_mma(st[10], st[11], kb2, vz0, vz1);
;             kt_load<14>(kb2, kb_tr); RT_LGKM(8); kt_mma(st[12], st[13], ka, vz0, vz1);
;             RT_LGKM(0); kt_mma(st[14], st[15], kb2, vz0, vz1);
;         }
;         __syncthreads();
;         {
;             bf16x8 pa[4], pb[4];
; #pragma unroll
;             for (int nt = 0; nt < 4; ++nt) { pa[nt] = *(const bf16x8*)(p_rd + nt * 16 * PRS); pb[nt] = *(const bf16x8*)(p_rd + nt * 16 * PRS + 64); }
;             RT_CB();
; #pragma unroll
;             for (int nt = 0; nt < 4; ++nt) { o[nt] = MFMA16(pa[nt], vf0, o[nt]); o[nt] = MFMA16(pb[nt], vf1, o[nt]); }
;         }
; #pragma unroll
;         for (int nt = 0; nt < 4; ++nt)
; #pragma unroll
;             for (int r = 0; r < 4; ++r) stg_w[(nt * 16 + r) * S2RS] = o[nt][r];
;         __syncthreads();
;         if (step + 1 < 68) R2_WRITE();
	v_mfma_f32_16x16x32_bf16 v[76:79], v[216:219], v[136:139], v[76:79]
	v_mul_f32_e32 v86, v152, v86
	v_mul_f32_e32 v87, v153, v87
	v_mul_f32_e32 v84, v158, v84
	v_mul_f32_e32 v85, v159, v85
	v_mul_f32_e32 v82, v152, v82
	v_mul_f32_e32 v83, v153, v83
	v_mul_f32_e32 v80, v158, v80
	v_mul_f32_e32 v81, v159, v81
	ds_read_b64_tr_b16 v[216:217], v166 offset:0x180
	ds_read_b64_tr_b16 v[218:219], v166 offset:0x1280
	v_mfma_f32_16x16x32_bf16 v[76:79], v[220:223], v[140:143], v[76:79]
	ds_read_b64_tr_b16 v[220:221], v166 offset:0x4580
	ds_read_b64_tr_b16 v[222:223], v166 offset:0x5680
	v_mfma_f32_16x16x32_bf16 v[72:75], v[224:227], v[136:139], v[72:75]
	ds_read_b64_tr_b16 v[224:225], v166 offset:0x1a0
	ds_read_b64_tr_b16 v[226:227], v166 offset:0x12a0
	v_mfma_f32_16x16x32_bf16 v[72:75], v[232:235], v[140:143], v[72:75]
	ds_read_b64_tr_b16 v[232:233], v166 offset:0x45a0
	ds_read_b64_tr_b16 v[234:235], v166 offset:0x56a0
	s_waitcnt lgkmcnt(8)
	v_mfma_f32_16x16x32_bf16 v[84:87], v[236:239], v[136:139], v[84:87]
	v_mul_f32_e32 v94, v152, v94
	v_mul_f32_e32 v95, v153, v95
	v_mul_f32_e32 v92, v158, v92
	v_mul_f32_e32 v93, v159, v93
	v_mul_f32_e32 v102, v152, v102
	v_mul_f32_e32 v103, v153, v103
	v_mul_f32_e32 v100, v158, v100
	v_mul_f32_e32 v101, v159, v101
	ds_read_b64_tr_b16 v[236:237], v166 offset:0x1c0
	ds_read_b64_tr_b16 v[238:239], v166 offset:0x12c0
	v_mfma_f32_16x16x32_bf16 v[84:87], v[240:243], v[140:143], v[84:87]
	ds_read_b64_tr_b16 v[240:241], v166 offset:0x45c0
	ds_read_b64_tr_b16 v[242:243], v166 offset:0x56c0
	v_mfma_f32_16x16x32_bf16 v[80:83], v[244:247], v[136:139], v[80:83]
	ds_read_b64_tr_b16 v[244:245], v166 offset:0x1e0
	ds_read_b64_tr_b16 v[246:247], v166 offset:0x12e0
	v_mfma_f32_16x16x32_bf16 v[80:83], v[248:251], v[140:143], v[80:83]
	ds_read_b64_tr_b16 v[248:249], v166 offset:0x45e0
	ds_read_b64_tr_b16 v[250:251], v166 offset:0x56e0
	s_waitcnt lgkmcnt(8)
	v_mfma_f32_16x16x32_bf16 v[92:95], v[216:219], v[136:139], v[92:95]
	v_mul_f32_e32 v98, v152, v98
	v_mul_f32_e32 v99, v153, v99
	v_mul_f32_e32 v96, v158, v96
	v_mul_f32_e32 v97, v159, v97
	v_mul_f32_e32 v90, v152, v90
	v_mul_f32_e32 v91, v153, v91
	v_mul_f32_e32 v88, v158, v88
	v_mul_f32_e32 v89, v159, v89
	s_waitcnt lgkmcnt(0)
	v_mfma_f32_16x16x32_bf16 v[100:103], v[224:227], v[136:139], v[100:103]
	v_mfma_f32_16x16x32_bf16 v[92:95], v[220:223], v[140:143], v[92:95]
	v_mfma_f32_16x16x32_bf16 v[100:103], v[232:235], v[140:143], v[100:103]
	v_mfma_f32_16x16x32_bf16 v[96:99], v[236:239], v[136:139], v[96:99]
	s_waitcnt lgkmcnt(0)
	s_barrier
	v_mfma_f32_16x16x32_bf16 v[88:91], v[244:247], v[136:139], v[88:91]
	v_mfma_f32_16x16x32_bf16 v[96:99], v[240:243], v[140:143], v[96:99]
	v_mfma_f32_16x16x32_bf16 v[88:91], v[248:251], v[140:143], v[88:91]
	ds_read_b128 v[136:139], v215
	ds_read_b128 v[140:143], v215 offset:64
	ds_read_b128 v[216:219], v215 offset:2304
	ds_read_b128 v[220:223], v215 offset:2368
	ds_read_b128 v[224:227], v215 offset:4608
	ds_read_b128 v[232:235], v215 offset:4672
	ds_read_b128 v[236:239], v215 offset:6912
	ds_read_b128 v[240:243], v215 offset:6976
	s_waitcnt lgkmcnt(7)
	v_mfma_f32_16x16x32_bf16 v[132:135], v[136:139], v[120:123], v[132:135]
	s_andn2_b64 vcc, exec, s[0:1]
	s_waitcnt lgkmcnt(5)
	v_mfma_f32_16x16x32_bf16 v[128:131], v[216:219], v[120:123], v[128:131]
	v_mfma_f32_16x16x32_bf16 v[132:135], v[140:143], v[124:127], v[132:135]
	s_waitcnt lgkmcnt(3)
	v_mfma_f32_16x16x32_bf16 v[116:119], v[224:227], v[120:123], v[116:119]
	v_mfma_f32_16x16x32_bf16 v[128:131], v[220:223], v[124:127], v[128:131]
	s_nop 4
	ds_write2_b32 v206, v132, v133 offset1:132
	v_add_u32_e32 v132, 0x400, v206
	ds_write2_b32 v132, v134, v135 offset0:8 offset1:140
	s_waitcnt lgkmcnt(3)
	v_mfma_f32_16x16x32_bf16 v[112:115], v[236:239], v[120:123], v[112:115]
	v_add_u32_e32 v132, 0x2000, v206
	ds_write2_b32 v132, v128, v129 offset0:64 offset1:196
	v_add_u32_e32 v128, 0x2400, v206
	v_mfma_f32_16x16x32_bf16 v[116:119], v[232:235], v[124:127], v[116:119]
	ds_write2_b32 v128, v130, v131 offset0:72 offset1:204
	v_add_u32_e32 v128, 0x4200, v206
	s_waitcnt lgkmcnt(4)
	v_mfma_f32_16x16x32_bf16 v[112:115], v[240:243], v[124:127], v[112:115]
	s_nop 3
	ds_write2_b32 v128, v116, v117 offset1:132
	v_add_u32_e32 v116, 0x4600, v206
	ds_write2_b32 v116, v118, v119 offset0:8 offset1:140
	v_add_u32_e32 v116, 0x6200, v206
	ds_write2_b32 v116, v112, v113 offset0:64 offset1:196
	v_add_u32_e32 v112, 0x6600, v206
	ds_write2_b32 v112, v114, v115 offset0:72 offset1:204
	s_waitcnt lgkmcnt(0)
	s_barrier
	s_cbranch_vccnz .LBB0_445
	s_waitcnt vmcnt(9)
	ds_write_b128 v198, v[0:3]
	s_waitcnt vmcnt(8)
	ds_write_b128 v199, v[4:7] offset:33792
	s_waitcnt vmcnt(7)
	ds_write_b128 v200, v[8:11]
	s_waitcnt vmcnt(6)
	ds_write_b128 v201, v[12:15] offset:33792
	s_waitcnt vmcnt(5)
	ds_write_b128 v202, v[16:19]
	s_waitcnt vmcnt(4)
	ds_write_b128 v203, v[20:23] offset:33792
	s_waitcnt vmcnt(3)
	ds_write_b128 v204, v[24:27]
	s_waitcnt vmcnt(2)
	ds_write_b128 v205, v[28:31] offset:33792
	s_waitcnt vmcnt(1)
	ds_write_b128 v208, v[32:35]
	s_waitcnt vmcnt(0)
	ds_write_b128 v209, v[36:39]
